# v1 plus 4-byte pads before the P8 and P9 phases so every GEMM K-loop head is 8-byte aligned
# speedup vs baseline: 1.0037x; 1.0037x over previous
;     __host__ __device__ bool next(int i, Unit& u) const {
;         const long L = (long)i * G + c; if (L >= nwg) return false;
;         int wgid = (int)L; { const int q = nwg / NXCD, r = nwg % NXCD, xcd = wgid % NXCD, off = wgid / NXCD; wgid = (xcd < r ? xcd * (q + 1) : r * (q + 1) + (xcd - r) * q) + off; }
;         const int nig = WGM * nN, gid = wgid / nig, fm = gid * WGM, gsz = (nM - fm) < WGM ? (nM - fm) : WGM;
;         u.pm = fm + ((wgid % nig) % gsz); u.pn = (wgid % nig) / gsz; return true;
; __global__ void __launch_bounds__(NTHR, 2) fwd_megakernel(Args args_unused) {
;     ...
;     xcd_barrier(xbar);
;     {
;         PH_COMMON
;         pg8::Gemm g{WSP(WS_U), WSP(WS_WGU), M, NGU, 2048}; pg8::StaticOrder S; S.init(M, NGU, G, bx);
;         epi::SwiGlu E{ws + WS_ACT, ACT_PITCH, FFN_H8, ACT_S8};
;         pg8::gemm_phase<epi::SwiGlu, pg8::StaticOrder, true, true>(lds, g, S, E);
.LBB0_712:
	s_or_b64 exec, exec, s[6:7]
	s_mov_b64 s[6:7], s[28:29]
	s_waitcnt lgkmcnt(0)
	v_mov_b32_e32 v0, v230
	v_mov_b32_e32 v8, v230
	s_cmpk_lt_i32 s2, 0x1600
	s_barrier
	s_nop 0
	s_cselect_b64 s[10:11], -1, 0
	s_cmpk_gt_i32 s2, 0x15ff
	v_readfirstlane_b32 s1, v8
	s_cbranch_scc1 .LBB0_714
	s_ashr_i32 s3, s2, 31
	s_lshr_b32 s3, s3, 29
	s_add_i32 s3, s2, s3
	s_ashr_i32 s8, s3, 3
	s_and_b32 s3, s3, -8
	s_sub_i32 s3, s2, s3
	s_cmp_lt_i32 s3, 0
	s_movk_i32 s9, 0x2c1
	s_cselect_b32 s9, s9, 0x2c0
	s_mul_i32 s3, s3, s9
	s_add_i32 s3, s3, s8
	s_mul_hi_i32 s8, s3, 0x2e8ba2e9
	s_lshr_b32 s9, s8, 31
	s_ashr_i32 s8, s8, 6
	s_add_i32 s8, s8, s9
	s_lshl_b32 s9, s8, 3
	s_mulk_i32 s8, 0x160
	s_sub_i32 s3, s3, s8
	s_sext_i32_i16 s8, s3
	s_bfe_u32 s8, s8, 0x3001c
	s_add_i32 s8, s3, s8
	s_sext_i32_i16 s12, s8
	s_and_b32 s8, s8, 0xfff8
	s_sub_i32 s3, s3, s8
	s_sext_i32_i16 s3, s3
	s_add_i32 s26, s9, s3
	s_ashr_i32 s8, s12, 3

; __global__ void __launch_bounds__(NTHR, 2) fwd_megakernel(Args args_unused) {
;     ...
;     xcd_barrier(xbar);
;     {
;         PH_COMMON
;         pg8::Gemm g{WSP(WS_ACT), WSP(WS_WD), M, 2048, ACT_PITCH / 2, FFN_T8}; pg8::StaticOrder S; S.init(M, 2048, G, bx);
;         epi::PlainMix E{WSP(WS_F), 2048, FFN_T8, 1.f / (ACT_S8 * WD_S8)};
.LBB0_814:
	s_or_b64 exec, exec, s[6:7]
	s_mov_b64 s[6:7], s[28:29]
	s_waitcnt lgkmcnt(0)
	v_mov_b32_e32 v0, v230
	v_mov_b32_e32 v8, v230
	s_barrier
	s_nop 0
	s_and_b64 vcc, exec, s[4:5]
	v_readfirstlane_b32 s1, v8
	s_cbranch_vccnz .LBB0_844
	s_ashr_i32 s3, s2, 31
	s_load_dwordx2 s[4:5], s[6:7], 0xe0
	s_lshr_b32 s6, s3, 29
	s_add_i32 s9, s2, s6
	s_and_b32 s6, s9, -8
	s_sub_i32 s10, s2, s6
	s_cmp_gt_i32 s10, -1
	s_cbranch_scc0 .LBB0_817
	s_lshl_b32 s8, s10, 7
	s_cbranch_execz .LBB0_818
	s_branch .LBB0_819
